# P5 forward substitution j-part on v_mfma_f32_4x4x1_16b_f32 (exact f32 fma, same order), 2 rows per trip, operands one row ahead; solved rows written out with wide stores after the unit barrier
# speedup vs baseline: 1.0513x; 1.0087x over previous
; __device__ __forceinline__ unsigned short f2bf(float f) { return (unsigned short)(cvt_pk_bf16(f, 0.f) & 0xffffu); }
; #define LDS_BARRIER() do { asm volatile("s_waitcnt lgkmcnt(0)" ::: "memory"); __builtin_amdgcn_s_barrier(); asm volatile("" ::: "memory"); } while (0)
; __device__ __forceinline__ void prep_unit(const int PREP_STEPS, LAS unsigned char* lds, int uidx, bf16* Qg, bf16* Kg, bf16* Vg, bf16* KT, bf16* QK, const bf16* HALO, const float* wconv, const float* BETA, const float* GG, float* GC) {
;     ...
;             for (int r = 0; r < 16; ++r) { const unsigned short ub = f2bf(au[r]), wb = f2bf(aw[r]); Vs[(16 * I + r) * 136 + c] = ub; Ks[(16 * I + r) * 136 + c] = wb;
;                 dstu[(size_t)(16 * I + r) * D] = ub; dstw[(size_t)(16 * I + r) * D] = wb; }
;         }
;         }
;     }
;     LDS_BARRIER();
.LBB0_637:
	s_or_b64 exec, exec, s[6:7]
	s_waitcnt lgkmcnt(0)
	s_barrier
	v_and_b32_e32 v32, 0xff, v154
	v_lshrrev_b32_e32 v33, 4, v32
	v_and_b32_e32 v34, 15, v32
	v_lshlrev_b32_e32 v34, 4, v34
	v_mul_u32_u24_e32 v35, 0x110, v33
	v_add3_u32 v35, v35, v34, v110
	v_add_u32_e32 v36, v70, v33
	v_lshl_add_u32 v36, v36, 11, v34
	v_add_u32_e32 v37, 0x8000, v36
	v_add_u32_e32 v38, 0x10000, v36
	v_add_u32_e32 v39, 0x18000, v36
	s_lshl_b32 s0, s82, 8
	s_add_u32 s12, s10, s0
	s_addc_u32 s13, s11, 0
	s_add_u32 s14, s8, s0
	s_addc_u32 s15, s9, 0
	ds_read_b128 v[0:3], v35 offset:34816
	ds_read_b128 v[4:7], v35 offset:39168
	ds_read_b128 v[8:11], v35 offset:43520
	ds_read_b128 v[12:15], v35 offset:47872
	ds_read_b128 v[16:19], v35 offset:17408
	ds_read_b128 v[20:23], v35 offset:21760
	ds_read_b128 v[24:27], v35 offset:26112
	ds_read_b128 v[28:31], v35 offset:30464
	s_waitcnt lgkmcnt(0)
	s_barrier
	global_store_dwordx4 v36, v[0:3], s[12:13]
	global_store_dwordx4 v37, v[4:7], s[12:13]
	global_store_dwordx4 v38, v[8:11], s[12:13]
	global_store_dwordx4 v39, v[12:15], s[12:13]
	global_store_dwordx4 v36, v[16:19], s[14:15]
	global_store_dwordx4 v37, v[20:23], s[14:15]
	global_store_dwordx4 v38, v[24:27], s[14:15]
	global_store_dwordx4 v39, v[28:31], s[14:15]
	s_add_i32 s3, s3, s88
	s_cmpk_gt_i32 s3, 0x3ff
	s_cbranch_scc1 .LBB0_768

; __device__ __forceinline__ float bf2f(unsigned short b) { return __uint_as_float((unsigned)b << 16); }
; __device__ __forceinline__ void prep_unit(const int PREP_STEPS, LAS unsigned char* lds, int uidx, bf16* Qg, bf16* Kg, bf16* Vg, bf16* KT, bf16* QK, const bf16* HALO, const float* wconv, const float* BETA, const float* GG, float* GC) {
;     ...
;     if (PREP_STEPS & 4) {
;         const bool active = hb == 0 ? (tl < 128) : (tl >= 128);
;         if (active) {
;         const int c = tl & 127;
;         bf16* dstu = Vg + (size_t)m0 * D + h * 128 + c; bf16* dstw = Kg + (size_t)m0 * D + h * 128 + c;
; #pragma unroll 1
;         for (int I = 0; I < 4; ++I) {
;             float au[16], aw[16];
; #pragma unroll
;             for (int r = 0; r < 16; ++r) { au[r] = bf2f(Vs[(16 * I + r) * 136 + c]) * betas[16 * I + r]; aw[r] = bf2f(Ks[(16 * I + r) * 136 + c]) * egcs[16 * I + r]; }
;             const int l16 = lane & 15;
; #pragma unroll 2
;             for (int j = 0; j < 16 * I; ++j) {
;                 const float xu = bf2f(Vs[j * 136 + c]), xw = bf2f(Ks[j * 136 + c]);
;                 const int av = __builtin_bit_cast(int, Af[j * 68 + 16 * I + l16]);
;                 Rows16<0>::run(av, xu, xw, au, aw, -1);
;             }
; #pragma unroll
;             for (int q = 0; q < 15; ++q) {
;                 const float xu = au[q], xw = aw[q];
;                 const int av = __builtin_bit_cast(int, Af[(16 * I + q) * 68 + 16 * I + l16]);
;                 Rows16<0>::run(av, xu, xw, au, aw, q);
.LBB0_762:
	s_waitcnt lgkmcnt(0)
	s_barrier
	s_mov_b64 s[6:7], exec
	s_and_b64 s[0:1], s[4:5], exec
	s_cmp_lg_u64 s[0:1], 0
	s_cselect_b32 s12, s10, s8
	s_cselect_b32 s13, s11, s9
	s_mov_b32 s14, 0x4400
	s_cselect_b32 s14, 0x8800, s14
	s_mov_b32 s15, 0x11200
	s_cselect_b32 s15, 0x11100, s15
	s_lshl_b32 s0, s82, 8
	s_add_u32 s12, s12, s0
	s_addc_u32 s13, s13, 0
	v_lshlrev_b32_e32 v16, 1, v56
	v_add_u32_e32 v16, v16, v110
	v_add_u32_e32 v16, s14, v16
	v_mov_b32_e32 v17, v16
	v_add_u32_e32 v48, s15, v110
	v_and_b32_e32 v49, 3, v154
	v_lshlrev_b32_e32 v49, 4, v49
	v_add_u32_e32 v49, v49, v110
	v_add_u32_e32 v49, 0xcc00, v49
	s_mov_b32 s1, 0
.Lfs_I:
	ds_read_b128 v[40:43], v48
	ds_read_b128 v[44:47], v48 offset:16
	ds_read_u16 v20, v17
	ds_read_u16 v21, v17 offset:272
	ds_read_u16 v22, v17 offset:544
	ds_read_u16 v23, v17 offset:816
	ds_read_u16 v24, v17 offset:1088
	ds_read_u16 v25, v17 offset:1360
	ds_read_u16 v26, v17 offset:1632
	ds_read_u16 v27, v17 offset:1904
	s_waitcnt lgkmcnt(0)
	v_lshlrev_b32_e32 v20, 16, v20
	v_lshlrev_b32_e32 v21, 16, v21
	v_lshlrev_b32_e32 v22, 16, v22
	v_lshlrev_b32_e32 v23, 16, v23
	v_lshlrev_b32_e32 v24, 16, v24
	v_lshlrev_b32_e32 v25, 16, v25
	v_lshlrev_b32_e32 v26, 16, v26
	v_lshlrev_b32_e32 v27, 16, v27
	v_mul_f32_e32 v0, v20, v40
	v_mul_f32_e32 v4, v21, v41
	v_mul_f32_e32 v8, v22, v42
	v_mul_f32_e32 v12, v23, v43
	v_mul_f32_e32 v1, v24, v44
	v_mul_f32_e32 v5, v25, v45
	v_mul_f32_e32 v9, v26, v46
	v_mul_f32_e32 v13, v27, v47
	ds_read_b128 v[40:43], v48 offset:32
	ds_read_b128 v[44:47], v48 offset:48
	ds_read_u16 v20, v17 offset:2176
	ds_read_u16 v21, v17 offset:2448
	ds_read_u16 v22, v17 offset:2720
	ds_read_u16 v23, v17 offset:2992
	ds_read_u16 v24, v17 offset:3264
	ds_read_u16 v25, v17 offset:3536
	ds_read_u16 v26, v17 offset:3808
	ds_read_u16 v27, v17 offset:4080
	s_waitcnt lgkmcnt(0)
	v_lshlrev_b32_e32 v20, 16, v20
	v_lshlrev_b32_e32 v21, 16, v21
	v_lshlrev_b32_e32 v22, 16, v22
	v_lshlrev_b32_e32 v23, 16, v23
	v_lshlrev_b32_e32 v24, 16, v24
	v_lshlrev_b32_e32 v25, 16, v25
	v_lshlrev_b32_e32 v26, 16, v26
	v_lshlrev_b32_e32 v27, 16, v27
	v_mul_f32_e32 v2, v20, v40
	v_mul_f32_e32 v6, v21, v41
	v_mul_f32_e32 v10, v22, v42
	v_mul_f32_e32 v14, v23, v43
	v_mul_f32_e32 v3, v24, v44
	v_mul_f32_e32 v7, v25, v45
	v_mul_f32_e32 v11, v26, v46
	v_mul_f32_e32 v15, v27, v47
	s_cmp_eq_u32 s1, 0
	s_cbranch_scc1 .Lfs_q
	s_lshl_b32 s0, s1, 3
	s_lshl_b32 s14, s1, 6
	v_mov_b32_e32 v18, v16
	v_add_u32_e32 v19, s14, v49
	ds_read_u16 v36, v18
	ds_read_b128 v[40:43], v19
	ds_read_u16 v37, v18 offset:272
	ds_read_b128 v[44:47], v19 offset:272
.Lfs_j:
	s_waitcnt lgkmcnt(2)
	v_lshlrev_b32_e32 v38, 16, v36
	v_add_u32_e32 v18, 0x220, v18
	v_add_u32_e32 v19, 0x220, v19
	v_mfma_f32_4x4x1_16b_f32 v[0:3], v40, v38, v[0:3]
	v_mfma_f32_4x4x1_16b_f32 v[4:7], v41, v38, v[4:7]
	v_mfma_f32_4x4x1_16b_f32 v[8:11], v42, v38, v[8:11]
	v_mfma_f32_4x4x1_16b_f32 v[12:15], v43, v38, v[12:15]
	ds_read_u16 v36, v18
	ds_read_b128 v[40:43], v19
	s_waitcnt lgkmcnt(2)
	v_lshlrev_b32_e32 v39, 16, v37
	s_nop 1
	v_mfma_f32_4x4x1_16b_f32 v[0:3], v44, v39, v[0:3]
	v_mfma_f32_4x4x1_16b_f32 v[4:7], v45, v39, v[4:7]
	v_mfma_f32_4x4x1_16b_f32 v[8:11], v46, v39, v[8:11]
	v_mfma_f32_4x4x1_16b_f32 v[12:15], v47, v39, v[12:15]
	ds_read_u16 v37, v18 offset:272
	ds_read_b128 v[44:47], v19 offset:272
	s_sub_i32 s0, s0, 1
	s_cmp_lg_u32 s0, 0
	s_cbranch_scc1 .Lfs_j
	s_waitcnt lgkmcnt(0)
	s_nop 4
.Lfs_q:
	s_mul_i32 s0, s1, 0x1140
	v_add_u32_e32 v19, s0, v145
	ds_read_b32 v20, v19
	ds_read_b32 v21, v19 offset:272
	ds_read_b32 v22, v19 offset:544
	ds_read_b32 v23, v19 offset:816
	ds_read_b32 v24, v19 offset:1088
	ds_read_b32 v25, v19 offset:1360
	ds_read_b32 v26, v19 offset:1632
	ds_read_b32 v27, v19 offset:1904
	ds_read_b32 v28, v19 offset:2176
	ds_read_b32 v29, v19 offset:2448
	ds_read_b32 v30, v19 offset:2720
	ds_read_b32 v31, v19 offset:2992
	ds_read_b32 v32, v19 offset:3264
	ds_read_b32 v33, v19 offset:3536
	ds_read_b32 v34, v19 offset:3808
	s_waitcnt lgkmcnt(14)
	v_fmac_f32_dpp v4, v20, v0 row_newbcast:1 row_mask:0xf bank_mask:0xf bound_ctrl:1
	v_fmac_f32_dpp v8, v20, v0 row_newbcast:2 row_mask:0xf bank_mask:0xf bound_ctrl:1
	v_fmac_f32_dpp v12, v20, v0 row_newbcast:3 row_mask:0xf bank_mask:0xf bound_ctrl:1
	v_fmac_f32_dpp v1, v20, v0 row_newbcast:4 row_mask:0xf bank_mask:0xf bound_ctrl:1
	v_fmac_f32_dpp v5, v20, v0 row_newbcast:5 row_mask:0xf bank_mask:0xf bound_ctrl:1
	v_fmac_f32_dpp v9, v20, v0 row_newbcast:6 row_mask:0xf bank_mask:0xf bound_ctrl:1
	v_fmac_f32_dpp v13, v20, v0 row_newbcast:7 row_mask:0xf bank_mask:0xf bound_ctrl:1
	v_fmac_f32_dpp v2, v20, v0 row_newbcast:8 row_mask:0xf bank_mask:0xf bound_ctrl:1
	v_fmac_f32_dpp v6, v20, v0 row_newbcast:9 row_mask:0xf bank_mask:0xf bound_ctrl:1
	v_fmac_f32_dpp v10, v20, v0 row_newbcast:10 row_mask:0xf bank_mask:0xf bound_ctrl:1
	v_fmac_f32_dpp v14, v20, v0 row_newbcast:11 row_mask:0xf bank_mask:0xf bound_ctrl:1
	v_fmac_f32_dpp v3, v20, v0 row_newbcast:12 row_mask:0xf bank_mask:0xf bound_ctrl:1
	v_fmac_f32_dpp v7, v20, v0 row_newbcast:13 row_mask:0xf bank_mask:0xf bound_ctrl:1
	v_fmac_f32_dpp v11, v20, v0 row_newbcast:14 row_mask:0xf bank_mask:0xf bound_ctrl:1
	v_fmac_f32_dpp v15, v20, v0 row_newbcast:15 row_mask:0xf bank_mask:0xf bound_ctrl:1
	s_waitcnt lgkmcnt(13)
; __device__ __forceinline__ void prep_unit(const int PREP_STEPS, LAS unsigned char* lds, int uidx, bf16* Qg, bf16* Kg, bf16* Vg, bf16* KT, bf16* QK, const bf16* HALO, const float* wconv, const float* BETA, const float* GG, float* GC) {
;     ...
;             for (int q = 0; q < 15; ++q) {
;                 const float xu = au[q], xw = aw[q];
;                 const int av = __builtin_bit_cast(int, Af[(16 * I + q) * 68 + 16 * I + l16]);
;                 Rows16<0>::run(av, xu, xw, au, aw, q);
;             }
	v_fmac_f32_dpp v8, v21, v4 row_newbcast:2 row_mask:0xf bank_mask:0xf bound_ctrl:1
	v_fmac_f32_dpp v12, v21, v4 row_newbcast:3 row_mask:0xf bank_mask:0xf bound_ctrl:1
	v_fmac_f32_dpp v1, v21, v4 row_newbcast:4 row_mask:0xf bank_mask:0xf bound_ctrl:1
	v_fmac_f32_dpp v5, v21, v4 row_newbcast:5 row_mask:0xf bank_mask:0xf bound_ctrl:1
	v_fmac_f32_dpp v9, v21, v4 row_newbcast:6 row_mask:0xf bank_mask:0xf bound_ctrl:1
	v_fmac_f32_dpp v13, v21, v4 row_newbcast:7 row_mask:0xf bank_mask:0xf bound_ctrl:1
	v_fmac_f32_dpp v2, v21, v4 row_newbcast:8 row_mask:0xf bank_mask:0xf bound_ctrl:1
	v_fmac_f32_dpp v6, v21, v4 row_newbcast:9 row_mask:0xf bank_mask:0xf bound_ctrl:1
	v_fmac_f32_dpp v10, v21, v4 row_newbcast:10 row_mask:0xf bank_mask:0xf bound_ctrl:1
	v_fmac_f32_dpp v14, v21, v4 row_newbcast:11 row_mask:0xf bank_mask:0xf bound_ctrl:1
	v_fmac_f32_dpp v3, v21, v4 row_newbcast:12 row_mask:0xf bank_mask:0xf bound_ctrl:1
	v_fmac_f32_dpp v7, v21, v4 row_newbcast:13 row_mask:0xf bank_mask:0xf bound_ctrl:1
	v_fmac_f32_dpp v11, v21, v4 row_newbcast:14 row_mask:0xf bank_mask:0xf bound_ctrl:1
	v_fmac_f32_dpp v15, v21, v4 row_newbcast:15 row_mask:0xf bank_mask:0xf bound_ctrl:1
	s_waitcnt lgkmcnt(12)
	v_fmac_f32_dpp v12, v22, v8 row_newbcast:3 row_mask:0xf bank_mask:0xf bound_ctrl:1
	v_fmac_f32_dpp v1, v22, v8 row_newbcast:4 row_mask:0xf bank_mask:0xf bound_ctrl:1
	v_fmac_f32_dpp v5, v22, v8 row_newbcast:5 row_mask:0xf bank_mask:0xf bound_ctrl:1
	v_fmac_f32_dpp v9, v22, v8 row_newbcast:6 row_mask:0xf bank_mask:0xf bound_ctrl:1
	v_fmac_f32_dpp v13, v22, v8 row_newbcast:7 row_mask:0xf bank_mask:0xf bound_ctrl:1
	v_fmac_f32_dpp v2, v22, v8 row_newbcast:8 row_mask:0xf bank_mask:0xf bound_ctrl:1
	v_fmac_f32_dpp v6, v22, v8 row_newbcast:9 row_mask:0xf bank_mask:0xf bound_ctrl:1
	v_fmac_f32_dpp v10, v22, v8 row_newbcast:10 row_mask:0xf bank_mask:0xf bound_ctrl:1
	v_fmac_f32_dpp v14, v22, v8 row_newbcast:11 row_mask:0xf bank_mask:0xf bound_ctrl:1
	v_fmac_f32_dpp v3, v22, v8 row_newbcast:12 row_mask:0xf bank_mask:0xf bound_ctrl:1
	v_fmac_f32_dpp v7, v22, v8 row_newbcast:13 row_mask:0xf bank_mask:0xf bound_ctrl:1
	v_fmac_f32_dpp v11, v22, v8 row_newbcast:14 row_mask:0xf bank_mask:0xf bound_ctrl:1
	v_fmac_f32_dpp v15, v22, v8 row_newbcast:15 row_mask:0xf bank_mask:0xf bound_ctrl:1
	s_waitcnt lgkmcnt(11)
	v_fmac_f32_dpp v1, v23, v12 row_newbcast:4 row_mask:0xf bank_mask:0xf bound_ctrl:1
	v_fmac_f32_dpp v5, v23, v12 row_newbcast:5 row_mask:0xf bank_mask:0xf bound_ctrl:1
	v_fmac_f32_dpp v9, v23, v12 row_newbcast:6 row_mask:0xf bank_mask:0xf bound_ctrl:1
	v_fmac_f32_dpp v13, v23, v12 row_newbcast:7 row_mask:0xf bank_mask:0xf bound_ctrl:1
	v_fmac_f32_dpp v2, v23, v12 row_newbcast:8 row_mask:0xf bank_mask:0xf bound_ctrl:1
	v_fmac_f32_dpp v6, v23, v12 row_newbcast:9 row_mask:0xf bank_mask:0xf bound_ctrl:1
	v_fmac_f32_dpp v10, v23, v12 row_newbcast:10 row_mask:0xf bank_mask:0xf bound_ctrl:1
	v_fmac_f32_dpp v14, v23, v12 row_newbcast:11 row_mask:0xf bank_mask:0xf bound_ctrl:1
	v_fmac_f32_dpp v3, v23, v12 row_newbcast:12 row_mask:0xf bank_mask:0xf bound_ctrl:1
	v_fmac_f32_dpp v7, v23, v12 row_newbcast:13 row_mask:0xf bank_mask:0xf bound_ctrl:1
	v_fmac_f32_dpp v11, v23, v12 row_newbcast:14 row_mask:0xf bank_mask:0xf bound_ctrl:1
	v_fmac_f32_dpp v15, v23, v12 row_newbcast:15 row_mask:0xf bank_mask:0xf bound_ctrl:1
	s_waitcnt lgkmcnt(10)
	v_fmac_f32_dpp v5, v24, v1 row_newbcast:5 row_mask:0xf bank_mask:0xf bound_ctrl:1
	v_fmac_f32_dpp v9, v24, v1 row_newbcast:6 row_mask:0xf bank_mask:0xf bound_ctrl:1
	v_fmac_f32_dpp v13, v24, v1 row_newbcast:7 row_mask:0xf bank_mask:0xf bound_ctrl:1
	v_fmac_f32_dpp v2, v24, v1 row_newbcast:8 row_mask:0xf bank_mask:0xf bound_ctrl:1
	v_fmac_f32_dpp v6, v24, v1 row_newbcast:9 row_mask:0xf bank_mask:0xf bound_ctrl:1
	v_fmac_f32_dpp v10, v24, v1 row_newbcast:10 row_mask:0xf bank_mask:0xf bound_ctrl:1
	v_fmac_f32_dpp v14, v24, v1 row_newbcast:11 row_mask:0xf bank_mask:0xf bound_ctrl:1
	v_fmac_f32_dpp v3, v24, v1 row_newbcast:12 row_mask:0xf bank_mask:0xf bound_ctrl:1
	v_fmac_f32_dpp v7, v24, v1 row_newbcast:13 row_mask:0xf bank_mask:0xf bound_ctrl:1
	v_fmac_f32_dpp v11, v24, v1 row_newbcast:14 row_mask:0xf bank_mask:0xf bound_ctrl:1
	v_fmac_f32_dpp v15, v24, v1 row_newbcast:15 row_mask:0xf bank_mask:0xf bound_ctrl:1
	s_waitcnt lgkmcnt(9)
	v_fmac_f32_dpp v9, v25, v5 row_newbcast:6 row_mask:0xf bank_mask:0xf bound_ctrl:1
	v_fmac_f32_dpp v13, v25, v5 row_newbcast:7 row_mask:0xf bank_mask:0xf bound_ctrl:1
	v_fmac_f32_dpp v2, v25, v5 row_newbcast:8 row_mask:0xf bank_mask:0xf bound_ctrl:1
	v_fmac_f32_dpp v6, v25, v5 row_newbcast:9 row_mask:0xf bank_mask:0xf bound_ctrl:1
	v_fmac_f32_dpp v10, v25, v5 row_newbcast:10 row_mask:0xf bank_mask:0xf bound_ctrl:1
	v_fmac_f32_dpp v14, v25, v5 row_newbcast:11 row_mask:0xf bank_mask:0xf bound_ctrl:1
	v_fmac_f32_dpp v3, v25, v5 row_newbcast:12 row_mask:0xf bank_mask:0xf bound_ctrl:1
	v_fmac_f32_dpp v7, v25, v5 row_newbcast:13 row_mask:0xf bank_mask:0xf bound_ctrl:1
	v_fmac_f32_dpp v11, v25, v5 row_newbcast:14 row_mask:0xf bank_mask:0xf bound_ctrl:1
	v_fmac_f32_dpp v15, v25, v5 row_newbcast:15 row_mask:0xf bank_mask:0xf bound_ctrl:1
	s_waitcnt lgkmcnt(8)
; __device__ __forceinline__ unsigned short f2bf(float f) { return (unsigned short)(cvt_pk_bf16(f, 0.f) & 0xffffu); }
; __device__ __forceinline__ void prep_unit(const int PREP_STEPS, LAS unsigned char* lds, int uidx, bf16* Qg, bf16* Kg, bf16* Vg, bf16* KT, bf16* QK, const bf16* HALO, const float* wconv, const float* BETA, const float* GG, float* GC) {
;     ...
; #pragma unroll
;             for (int q = 0; q < 15; ++q) {
;                 const float xu = au[q], xw = aw[q];
;                 const int av = __builtin_bit_cast(int, Af[(16 * I + q) * 68 + 16 * I + l16]);
;                 Rows16<0>::run(av, xu, xw, au, aw, q);
;             }
; #pragma unroll
;             for (int r = 0; r < 16; ++r) { const unsigned short ub = f2bf(au[r]), wb = f2bf(aw[r]); Vs[(16 * I + r) * 136 + c] = ub; Ks[(16 * I + r) * 136 + c] = wb;
;                 dstu[(size_t)(16 * I + r) * D] = ub; dstw[(size_t)(16 * I + r) * D] = wb; }
;         }
;         }
;     }
	v_fmac_f32_dpp v13, v26, v9 row_newbcast:7 row_mask:0xf bank_mask:0xf bound_ctrl:1
	v_fmac_f32_dpp v2, v26, v9 row_newbcast:8 row_mask:0xf bank_mask:0xf bound_ctrl:1
	v_fmac_f32_dpp v6, v26, v9 row_newbcast:9 row_mask:0xf bank_mask:0xf bound_ctrl:1
	v_fmac_f32_dpp v10, v26, v9 row_newbcast:10 row_mask:0xf bank_mask:0xf bound_ctrl:1
	v_fmac_f32_dpp v14, v26, v9 row_newbcast:11 row_mask:0xf bank_mask:0xf bound_ctrl:1
	v_fmac_f32_dpp v3, v26, v9 row_newbcast:12 row_mask:0xf bank_mask:0xf bound_ctrl:1
	v_fmac_f32_dpp v7, v26, v9 row_newbcast:13 row_mask:0xf bank_mask:0xf bound_ctrl:1
	v_fmac_f32_dpp v11, v26, v9 row_newbcast:14 row_mask:0xf bank_mask:0xf bound_ctrl:1
	v_fmac_f32_dpp v15, v26, v9 row_newbcast:15 row_mask:0xf bank_mask:0xf bound_ctrl:1
	s_waitcnt lgkmcnt(7)
	v_fmac_f32_dpp v2, v27, v13 row_newbcast:8 row_mask:0xf bank_mask:0xf bound_ctrl:1
	v_fmac_f32_dpp v6, v27, v13 row_newbcast:9 row_mask:0xf bank_mask:0xf bound_ctrl:1
	v_fmac_f32_dpp v10, v27, v13 row_newbcast:10 row_mask:0xf bank_mask:0xf bound_ctrl:1
	v_fmac_f32_dpp v14, v27, v13 row_newbcast:11 row_mask:0xf bank_mask:0xf bound_ctrl:1
	v_fmac_f32_dpp v3, v27, v13 row_newbcast:12 row_mask:0xf bank_mask:0xf bound_ctrl:1
	v_fmac_f32_dpp v7, v27, v13 row_newbcast:13 row_mask:0xf bank_mask:0xf bound_ctrl:1
	v_fmac_f32_dpp v11, v27, v13 row_newbcast:14 row_mask:0xf bank_mask:0xf bound_ctrl:1
	v_fmac_f32_dpp v15, v27, v13 row_newbcast:15 row_mask:0xf bank_mask:0xf bound_ctrl:1
	s_waitcnt lgkmcnt(6)
	v_fmac_f32_dpp v6, v28, v2 row_newbcast:9 row_mask:0xf bank_mask:0xf bound_ctrl:1
	v_fmac_f32_dpp v10, v28, v2 row_newbcast:10 row_mask:0xf bank_mask:0xf bound_ctrl:1
	v_fmac_f32_dpp v14, v28, v2 row_newbcast:11 row_mask:0xf bank_mask:0xf bound_ctrl:1
	v_fmac_f32_dpp v3, v28, v2 row_newbcast:12 row_mask:0xf bank_mask:0xf bound_ctrl:1
	v_fmac_f32_dpp v7, v28, v2 row_newbcast:13 row_mask:0xf bank_mask:0xf bound_ctrl:1
	v_fmac_f32_dpp v11, v28, v2 row_newbcast:14 row_mask:0xf bank_mask:0xf bound_ctrl:1
	v_fmac_f32_dpp v15, v28, v2 row_newbcast:15 row_mask:0xf bank_mask:0xf bound_ctrl:1
	s_waitcnt lgkmcnt(5)
	v_fmac_f32_dpp v10, v29, v6 row_newbcast:10 row_mask:0xf bank_mask:0xf bound_ctrl:1
	v_fmac_f32_dpp v14, v29, v6 row_newbcast:11 row_mask:0xf bank_mask:0xf bound_ctrl:1
	v_fmac_f32_dpp v3, v29, v6 row_newbcast:12 row_mask:0xf bank_mask:0xf bound_ctrl:1
	v_fmac_f32_dpp v7, v29, v6 row_newbcast:13 row_mask:0xf bank_mask:0xf bound_ctrl:1
	v_fmac_f32_dpp v11, v29, v6 row_newbcast:14 row_mask:0xf bank_mask:0xf bound_ctrl:1
	v_fmac_f32_dpp v15, v29, v6 row_newbcast:15 row_mask:0xf bank_mask:0xf bound_ctrl:1
	s_waitcnt lgkmcnt(4)
	v_fmac_f32_dpp v14, v30, v10 row_newbcast:11 row_mask:0xf bank_mask:0xf bound_ctrl:1
	v_fmac_f32_dpp v3, v30, v10 row_newbcast:12 row_mask:0xf bank_mask:0xf bound_ctrl:1
	v_fmac_f32_dpp v7, v30, v10 row_newbcast:13 row_mask:0xf bank_mask:0xf bound_ctrl:1
	v_fmac_f32_dpp v11, v30, v10 row_newbcast:14 row_mask:0xf bank_mask:0xf bound_ctrl:1
	v_fmac_f32_dpp v15, v30, v10 row_newbcast:15 row_mask:0xf bank_mask:0xf bound_ctrl:1
	s_waitcnt lgkmcnt(3)
	v_fmac_f32_dpp v3, v31, v14 row_newbcast:12 row_mask:0xf bank_mask:0xf bound_ctrl:1
	v_fmac_f32_dpp v7, v31, v14 row_newbcast:13 row_mask:0xf bank_mask:0xf bound_ctrl:1
	v_fmac_f32_dpp v11, v31, v14 row_newbcast:14 row_mask:0xf bank_mask:0xf bound_ctrl:1
	v_fmac_f32_dpp v15, v31, v14 row_newbcast:15 row_mask:0xf bank_mask:0xf bound_ctrl:1
	s_waitcnt lgkmcnt(2)
	v_fmac_f32_dpp v7, v32, v3 row_newbcast:13 row_mask:0xf bank_mask:0xf bound_ctrl:1
	v_fmac_f32_dpp v11, v32, v3 row_newbcast:14 row_mask:0xf bank_mask:0xf bound_ctrl:1
	v_fmac_f32_dpp v15, v32, v3 row_newbcast:15 row_mask:0xf bank_mask:0xf bound_ctrl:1
	s_waitcnt lgkmcnt(1)
	v_fmac_f32_dpp v11, v33, v7 row_newbcast:14 row_mask:0xf bank_mask:0xf bound_ctrl:1
	v_fmac_f32_dpp v15, v33, v7 row_newbcast:15 row_mask:0xf bank_mask:0xf bound_ctrl:1
	s_waitcnt lgkmcnt(0)
	v_fmac_f32_dpp v15, v34, v11 row_newbcast:15 row_mask:0xf bank_mask:0xf bound_ctrl:1
	v_cvt_pk_bf16_f32 v20, v0, v0
	v_cvt_pk_bf16_f32 v21, v4, v4
	v_cvt_pk_bf16_f32 v22, v8, v8
	v_cvt_pk_bf16_f32 v23, v12, v12
	v_cvt_pk_bf16_f32 v24, v1, v1
	v_cvt_pk_bf16_f32 v25, v5, v5
	v_cvt_pk_bf16_f32 v26, v9, v9
	v_cvt_pk_bf16_f32 v27, v13, v13
	v_cvt_pk_bf16_f32 v28, v2, v2
	v_cvt_pk_bf16_f32 v29, v6, v6
	v_cvt_pk_bf16_f32 v30, v10, v10
	v_cvt_pk_bf16_f32 v31, v14, v14
	v_cvt_pk_bf16_f32 v32, v3, v3
	v_cvt_pk_bf16_f32 v33, v7, v7
	v_cvt_pk_bf16_f32 v34, v11, v11
	v_cvt_pk_bf16_f32 v35, v15, v15
	ds_write_b16 v17, v20
	ds_write_b16 v17, v21 offset:272
	ds_write_b16 v17, v22 offset:544
	ds_write_b16 v17, v23 offset:816
	ds_write_b16 v17, v24 offset:1088
	ds_write_b16 v17, v25 offset:1360
	ds_write_b16 v17, v26 offset:1632
	ds_write_b16 v17, v27 offset:1904
	ds_write_b16 v17, v28 offset:2176
	ds_write_b16 v17, v29 offset:2448
	ds_write_b16 v17, v30 offset:2720
	ds_write_b16 v17, v31 offset:2992
	ds_write_b16 v17, v32 offset:3264
	ds_write_b16 v17, v33 offset:3536
	ds_write_b16 v17, v34 offset:3808
	ds_write_b16 v17, v35 offset:4080
	v_add_u32_e32 v17, 0x1100, v17
	v_add_u32_e32 v48, 64, v48
	s_add_i32 s1, s1, 1
	s_cmp_lg_u32 s1, 4
	s_cbranch_scc1 .Lfs_I
	s_branch .LBB0_637
